# FFT stage-2 DFT table staged once per phase in LDS; fft2m B fragments via ds_read_b128 instead of uncoalesced global loads
# speedup vs baseline: 1.1209x; 1.0156x over previous
.LBB0_399:
	s_and_b64 vcc, exec, s[0:1]
	s_cbranch_vccz .LBB0_446
	s_cmp_gt_i32 s18, 0
	s_mov_b64 s[0:1], -1
	s_cbranch_scc0 .LBB0_560
	s_cmp_gt_i32 s18, 1
	s_cbranch_scc0 .LBB0_448
	v_lshlrev_b32_e32 v64, 4, v0
	v_readlane_b32 s4, v253, 43
	v_readlane_b32 s5, v253, 44
	v_lshrrev_b32_e32 v65, 4, v0
	v_and_b32_e32 v76, 15, v0
	v_mul_u32_u24_e32 v65, 0x110, v65
	v_lshl_add_u32 v65, v76, 4, v65
	v_add_u32_e32 v65, 0x9800, v65
	s_nop 4
	global_load_dwordx4 v[72:75], v64, s[4:5]
	v_add_u32_e32 v76, 0x1000, v64
	global_load_dwordx4 v[84:87], v76, s[4:5]
	v_add_u32_e32 v76, 0x2000, v64
	global_load_dwordx4 v[88:91], v76, s[4:5]
	v_add_u32_e32 v76, 0x3000, v64
	global_load_dwordx4 v[92:95], v76, s[4:5]
	v_add_u32_e32 v76, 0x4000, v64
	global_load_dwordx4 v[96:99], v76, s[4:5]
	v_add_u32_e32 v76, 0x5000, v64
	global_load_dwordx4 v[100:103], v76, s[4:5]
	v_add_u32_e32 v76, 0x6000, v64
	global_load_dwordx4 v[104:107], v76, s[4:5]
	v_add_u32_e32 v76, 0x7000, v64
	global_load_dwordx4 v[108:111], v76, s[4:5]
	s_waitcnt vmcnt(0)
	ds_write_b128 v65, v[72:75]
	ds_write_b128 v65, v[84:87] offset:4352
	ds_write_b128 v65, v[88:91] offset:8704
	ds_write_b128 v65, v[92:95] offset:13056
	ds_write_b128 v65, v[96:99] offset:17408
	ds_write_b128 v65, v[100:103] offset:21760
	ds_write_b128 v65, v[104:107] offset:26112
	ds_write_b128 v65, v[108:111] offset:30464
	s_waitcnt lgkmcnt(0)
	s_barrier
	s_and_saveexec_b64 s[0:1], s[12:13]
	v_readlane_b32 s14, v254, 52
	v_readlane_b32 s15, v254, 53
	s_cbranch_execz .LBB0_406
	s_mov_b64 s[4:5], exec
	v_mbcnt_lo_u32_b32 v1, s4, 0
	v_mbcnt_hi_u32_b32 v1, s5, v1
	v_cmp_eq_u32_e32 vcc, 0, v1
	s_and_saveexec_b64 s[2:3], vcc
	s_cbranch_execz .LBB0_405
	s_bcnt1_i32_b64 s4, s[4:5]
	s_waitcnt vmcnt(0)
	v_mov_b32_e32 v2, s4
	v_readlane_b32 s4, v254, 43
	v_readlane_b32 s5, v254, 44
	s_nop 4
	global_atomic_add v2, v131, v2, s[4:5] sc0

.LBB0_410:
	s_cmp_gt_i32 s2, 63
	s_mov_b64 s[0:1], -1
	s_cbranch_scc0 .LBB0_432
	s_cmpk_gt_u32 s2, 0x8bf
	s_cbranch_scc0 .LBB0_419
	s_cmpk_gt_u32 s2, 0x10bf
	s_cbranch_scc0 .LBB0_416
	s_andn2_b64 vcc, exec, s[14:15]
	s_cbranch_vccnz .LBB0_415
	s_lshl_b32 s0, s2, 3
	s_and_b32 s0, s0, 0x7fffffc0
	v_mov_b32_e32 v18, v0
	s_addk_i32 s0, 0xba00
	s_lshl_b32 s1, s2, 6
	v_lshlrev_b32_e32 v1, 3, v18
	s_waitcnt vmcnt(0) lgkmcnt(0)
	v_ashrrev_i32_e32 v64, 3, v18
	s_and_b32 s18, s1, 0x1c0
	v_and_b32_e32 v65, 56, v1
	v_add_u32_e32 v72, s0, v64
	v_add_u32_e32 v64, 0x100, v18
	v_or_b32_e32 v73, s18, v65
	v_ashrrev_i32_e32 v65, 31, v72
	v_ashrrev_i32_e32 v74, 3, v64
	v_mov_b32_e32 v82, v72
	v_mov_b32_e32 v83, v65
	v_lshlrev_b64 v[84:85], 10, v[82:83]
	v_lshlrev_b32_e32 v64, 1, v73
	v_readlane_b32 s18, v253, 53
	v_add_u32_e32 v65, s0, v74
	v_or_b32_e32 v72, v84, v64
	v_readlane_b32 s19, v253, 54
	v_ashrrev_i32_e32 v73, 31, v65
	v_mov_b32_e32 v74, v65
	v_mov_b32_e32 v75, v73
	v_lshlrev_b64 v[82:83], 10, v[74:75]
	v_mov_b32_e32 v74, v72
	v_mov_b32_e32 v75, v85
	v_lshl_add_u64 v[86:87], s[18:19], 0, v[74:75]
	global_load_dwordx4 v[88:91], v[86:87], off
	v_or_b32_e32 v65, v82, v64
	v_mov_b32_e32 v74, v65
	v_mov_b32_e32 v75, v83
	v_lshl_add_u64 v[86:87], s[18:19], 0, v[74:75]
	global_load_dwordx4 v[92:95], v[86:87], off
	v_readlane_b32 s18, v254, 7
	v_readlane_b32 s19, v254, 8
	v_mov_b32_e32 v74, v72
	v_mov_b32_e32 v75, v85
	v_lshl_add_u64 v[86:87], s[18:19], 0, v[74:75]
	global_load_dwordx4 v[72:75], v[86:87], off
	v_mov_b32_e32 v84, v65
	v_mov_b32_e32 v85, v83
	v_lshl_add_u64 v[86:87], s[18:19], 0, v[84:85]
	global_load_dwordx4 v[82:85], v[86:87], off
	v_bfe_u32 v64, v18, 4, 2
	v_lshlrev_b32_e32 v65, 4, v64
	v_and_b32_e32 v64, 15, v18
	v_readlane_b32 s18, v253, 43
	v_readlane_b32 s19, v253, 44
	v_mov_b32_e32 v76, v131
	v_mov_b32_e32 v86, v65
	v_mov_b32_e32 v87, v131
	v_lshl_add_u64 v[96:97], s[18:19], 0, v[86:87]
	v_lshlrev_b32_e32 v65, 8, v64
	v_or_b32_e32 v64, 0x2000, v65
	v_mov_b32_e32 v86, v65
	v_mov_b32_e32 v87, v131
	v_lshl_add_u64 v[98:99], v[96:97], 0, v[86:87]
	v_mov_b32_e32 v86, v64
	v_mov_b32_e32 v87, v76
	v_lshl_add_u64 v[100:101], v[96:97], 0, v[86:87]
	v_and_b32_e32 v251, 15, v0
	v_mul_u32_u24_e32 v251, 0x110, v251
	v_bfe_u32 v250, v0, 4, 2
	v_lshl_add_u32 v251, v250, 4, v251
	v_add_u32_e32 v251, 0x9800, v251
	ds_read_b128 v[102:105], v251
	ds_read_b128 v[106:109], v251 offset:8704
	v_or_b32_e32 v78, 0x1000, v65
	v_mov_b32_e32 v86, v131
	v_lshl_add_u64 v[100:101], v[96:97], 0, 64
	v_mov_b32_e32 v110, v78
	v_mov_b32_e32 v111, v86
	v_lshl_add_u64 v[112:113], v[96:97], 0, v[110:111]
	ds_read_b128 v[114:117], v251 offset:4352
	ds_read_b128 v[110:113], v251 offset:64
	v_or_b32_e32 v87, 0x3000, v65
	v_mov_b32_e32 v98, v131
	v_mov_b32_e32 v118, v87
	v_mov_b32_e32 v119, v98
	v_lshl_add_u64 v[120:121], v[96:97], 0, v[118:119]
	ds_read_b128 v[122:125], v251 offset:13056
	v_or_b32_e32 v99, 0x4000, v65
	v_mov_b32_e32 v118, v131
	v_mov_b32_e32 v120, v99
	v_mov_b32_e32 v121, v118
	v_lshl_add_u64 v[126:127], v[96:97], 0, v[120:121]
	ds_read_b128 v[138:141], v251 offset:17408
	v_or_b32_e32 v119, 0x5000, v65
	v_mov_b32_e32 v120, v131
	v_mov_b32_e32 v126, v119
	v_mov_b32_e32 v127, v120
	v_lshl_add_u64 v[128:129], v[96:97], 0, v[126:127]
	ds_read_b128 v[142:145], v251 offset:21760
	v_or_b32_e32 v121, 0x6000, v65
	v_mov_b32_e32 v126, v131
	v_or_b32_e32 v127, 0x7000, v65
	v_mov_b32_e32 v128, v121
	v_mov_b32_e32 v129, v126
	v_lshl_add_u64 v[146:147], v[96:97], 0, v[128:129]
	v_mov_b32_e32 v128, v127
	v_mov_b32_e32 v129, v131
	v_lshl_add_u64 v[148:149], v[96:97], 0, v[128:129]
	ds_read_b128 v[126:129], v251 offset:26112
	ds_read_b128 v[150:153], v251 offset:30464
	v_mov_b32_e32 v96, v78
	v_mov_b32_e32 v97, v86
	v_lshl_add_u64 v[146:147], v[100:101], 0, v[96:97]
	ds_read_b128 v[154:157], v251 offset:4416
	v_mov_b32_e32 v96, v64
	v_mov_b32_e32 v97, v76
	v_lshl_add_u64 v[146:147], v[100:101], 0, v[96:97]
	ds_read_b128 v[162:165], v251 offset:8768
	v_mov_b32_e32 v64, v87
	v_mov_b32_e32 v65, v98
	v_lshl_add_u64 v[96:97], v[100:101], 0, v[64:65]
	ds_read_b128 v[146:149], v251 offset:13120
	v_mov_b32_e32 v64, v99
	v_mov_b32_e32 v65, v118
	v_lshl_add_u64 v[86:87], v[100:101], 0, v[64:65]
	ds_read_b128 v[96:99], v251 offset:17472
	v_mov_b32_e32 v64, v119
	v_mov_b32_e32 v65, v120
	v_lshl_add_u64 v[86:87], v[100:101], 0, v[64:65]
	ds_read_b128 v[118:121], v251 offset:21824
	v_ashrrev_i32_e32 v20, 3, v18
	s_and_b32 s1, s1, 0x1c0
	v_and_b32_e32 v19, 56, v1
	v_add_u32_e32 v2, s0, v20
	v_add_u32_e32 v10, 0x100, v18
	v_or_b32_e32 v1, s1, v19
	v_ashrrev_i32_e32 v3, 31, v2
	v_ashrrev_i32_e32 v21, 3, v10
	v_lshlrev_b64 v[6:7], 10, v[2:3]
	v_lshlrev_b32_e32 v1, 1, v1
	v_readlane_b32 s6, v253, 53
	v_add_u32_e32 v10, s0, v21
	v_or_b32_e32 v6, v6, v1
	v_readlane_b32 s7, v253, 54
	v_ashrrev_i32_e32 v11, 31, v10
	v_lshlrev_b64 v[14:15], 10, v[10:11]
	v_lshl_add_u64 v[2:3], s[6:7], 0, v[6:7]
	v_or_b32_e32 v14, v14, v1
	v_lshl_add_u64 v[10:11], s[6:7], 0, v[14:15]
	v_readlane_b32 s8, v254, 7
	v_readlane_b32 s9, v254, 8
	v_lshlrev_b32_e32 v20, 1, v20
	s_movk_i32 s3, 0x110
	v_lshl_add_u64 v[6:7], s[8:9], 0, v[6:7]
	v_lshl_add_u64 v[14:15], s[8:9], 0, v[14:15]
	v_mad_u32_u24 v20, v19, s3, v20
	s_barrier
	v_bfe_u32 v1, v18, 4, 2
	v_lshlrev_b32_e32 v130, 4, v1
	v_and_b32_e32 v28, 15, v18
	s_waitcnt vmcnt(0) lgkmcnt(0)
	ds_write_b16 v20, v88
	ds_write_b16_d16_hi v20, v88 offset:272
	ds_write_b16 v20, v89 offset:544
	ds_write_b16_d16_hi v20, v89 offset:816
	ds_write_b16 v20, v90 offset:1088
	ds_write_b16_d16_hi v20, v90 offset:1360
	ds_write_b16 v20, v91 offset:1632
	ds_write_b16_d16_hi v20, v91 offset:1904
	ds_write_b16 v20, v72 offset:128
	ds_write_b16_d16_hi v20, v72 offset:400
	ds_write_b16 v20, v73 offset:672
	ds_write_b16_d16_hi v20, v73 offset:944
	ds_write_b16 v20, v74 offset:1216
	ds_write_b16_d16_hi v20, v74 offset:1488
	ds_write_b16 v20, v75 offset:1760
	ds_write_b16_d16_hi v20, v75 offset:2032
	v_lshlrev_b32_e32 v2, 1, v21
	v_mad_u32_u24 v2, v19, s3, v2
	ds_write_b16 v2, v92
	ds_write_b16_d16_hi v2, v92 offset:272
	ds_write_b16 v2, v93 offset:544
	ds_write_b16_d16_hi v2, v93 offset:816
	ds_write_b16 v2, v94 offset:1088
	ds_write_b16_d16_hi v2, v94 offset:1360
	ds_write_b16 v2, v95 offset:1632
	ds_write_b16_d16_hi v2, v95 offset:1904
	ds_write_b16 v2, v82 offset:128
	ds_write_b16_d16_hi v2, v82 offset:400
	ds_write_b16 v2, v83 offset:672
	ds_write_b16_d16_hi v2, v83 offset:944
	ds_write_b16 v2, v84 offset:1216
	ds_write_b16_d16_hi v2, v84 offset:1488
	ds_write_b16 v2, v85 offset:1760
	ds_write_b16_d16_hi v2, v85 offset:2032
	v_ashrrev_i32_e32 v2, 2, v18
	v_and_b32_e32 v29, -16, v2
	v_bfi_b32 v2, -16, v2, v18
	v_mad_u64_u32 v[12:13], s[4:5], v2, s3, v[130:131]
	v_readlane_b32 s4, v253, 43
	v_readlane_b32 s5, v253, 44
	v_mov_b32_e32 v17, v131
	s_waitcnt lgkmcnt(0)
	v_lshl_add_u64 v[14:15], s[4:5], 0, v[130:131]
	v_lshlrev_b32_e32 v130, 8, v28
	v_or_b32_e32 v16, 0x2000, v130
	v_lshl_add_u64 v[10:11], v[14:15], 0, v[130:131]
	v_lshl_add_u64 v[20:21], v[14:15], 0, v[16:17]
	s_barrier
	ds_read_b128 v[2:5], v12
	v_or_b32_e32 v18, 0x1000, v130
	v_mov_b32_e32 v19, v131
	v_lshl_add_u64 v[62:63], v[14:15], 0, 64
	s_mov_b64 s[4:5], 0x80
	s_waitcnt lgkmcnt(0)
	v_mfma_f32_16x16x32_bf16 v[30:33], v[2:5], v[102:105], 0
	v_lshl_add_u64 v[6:7], v[14:15], 0, v[18:19]
	s_nop 0
	v_mfma_f32_16x16x32_bf16 v[34:37], v[2:5], v[106:109], 0
	v_or_b32_e32 v20, 0x3000, v130
	v_mov_b32_e32 v21, v131
	v_lshl_add_u64 v[22:23], v[14:15], 0, v[20:21]
	v_mfma_f32_16x16x32_bf16 v[6:9], v[2:5], v[114:117], 0
	v_mfma_f32_16x16x32_bf16 v[38:41], v[2:5], v[122:125], 0
	v_or_b32_e32 v22, 0x4000, v130
	v_mov_b32_e32 v23, v131
	v_lshl_add_u64 v[24:25], v[14:15], 0, v[22:23]
	v_mfma_f32_16x16x32_bf16 v[42:45], v[2:5], v[138:141], 0
	v_or_b32_e32 v26, 0x5000, v130
	v_mov_b32_e32 v27, v131
	v_lshl_add_u64 v[24:25], v[14:15], 0, v[26:27]
	v_or_b32_e32 v24, 0x6000, v130
	v_mov_b32_e32 v25, v131
	v_or_b32_e32 v130, 0x7000, v130
	v_lshl_add_u64 v[50:51], v[14:15], 0, v[24:25]
	v_lshl_add_u64 v[54:55], v[14:15], 0, v[130:131]
	v_mfma_f32_16x16x32_bf16 v[46:49], v[2:5], v[142:145], 0
	v_mfma_f32_16x16x32_bf16 v[50:53], v[2:5], v[126:129], 0
	v_mfma_f32_16x16x32_bf16 v[2:5], v[2:5], v[150:153], 0
	ds_read_b128 v[54:57], v12 offset:64
	s_waitcnt lgkmcnt(0)
	v_mfma_f32_16x16x32_bf16 v[30:33], v[54:57], v[110:113], v[30:33]
	v_lshl_add_u64 v[58:59], v[62:63], 0, v[18:19]
	v_mfma_f32_16x16x32_bf16 v[6:9], v[54:57], v[154:157], v[6:9]
	v_lshl_add_u64 v[58:59], v[62:63], 0, v[16:17]
	v_mfma_f32_16x16x32_bf16 v[34:37], v[54:57], v[162:165], v[34:37]
	v_lshl_add_u64 v[58:59], v[62:63], 0, v[20:21]
	v_mfma_f32_16x16x32_bf16 v[38:41], v[54:57], v[146:149], v[38:41]
	v_lshl_add_u64 v[58:59], v[62:63], 0, v[22:23]
	v_mfma_f32_16x16x32_bf16 v[42:45], v[54:57], v[96:99], v[42:45]
	v_lshl_add_u64 v[58:59], v[62:63], 0, v[26:27]
	v_mfma_f32_16x16x32_bf16 v[46:49], v[54:57], v[118:121], v[46:49]
	v_lshl_add_u64 v[58:59], v[62:63], 0, v[24:25]
	ds_read_b128 v[72:75], v251 offset:26176
	v_lshl_add_u64 v[64:65], v[62:63], 0, v[130:131]
	ds_read_b128 v[82:85], v251 offset:30528
	v_lshl_add_u64 v[64:65], v[14:15], 0, s[4:5]
	ds_read_b128 v[86:89], v251 offset:128
	s_mov_b64 s[18:19], 0xc0
	v_lshl_add_u64 v[90:91], v[64:65], 0, v[18:19]
	ds_read_b128 v[92:95], v251 offset:4480
	v_lshl_add_u64 v[90:91], v[64:65], 0, v[16:17]
	ds_read_b128 v[96:99], v251 offset:8832
	v_lshl_add_u64 v[90:91], v[64:65], 0, v[20:21]
	ds_read_b128 v[100:103], v251 offset:13184
	v_lshl_add_u64 v[90:91], v[64:65], 0, v[22:23]
	ds_read_b128 v[104:107], v251 offset:17536
	v_lshl_add_u64 v[90:91], v[64:65], 0, v[26:27]
	ds_read_b128 v[108:111], v251 offset:21888
	v_lshl_add_u64 v[90:91], v[64:65], 0, v[24:25]
	ds_read_b128 v[112:115], v251 offset:26240
	v_lshl_add_u64 v[90:91], v[64:65], 0, v[130:131]
	ds_read_b128 v[116:119], v251 offset:30592
	ds_read_b128 v[120:123], v251 offset:192
	v_lshl_add_u64 v[64:65], v[14:15], 0, s[18:19]
	v_lshl_add_u64 v[90:91], v[64:65], 0, v[18:19]
	v_lshl_add_u64 v[124:125], v[64:65], 0, v[20:21]
	ds_read_b128 v[126:129], v251 offset:13248
	ds_read_b128 v[138:141], v251 offset:4544
	v_lshl_add_u64 v[90:91], v[64:65], 0, v[16:17]
	ds_read_b128 v[142:145], v251 offset:8896
	v_lshl_add_u64 v[90:91], v[64:65], 0, v[22:23]
	ds_read_b128 v[146:149], v251 offset:17600
	v_lshl_add_u64 v[90:91], v[64:65], 0, v[26:27]
	v_lshl_add_u64 v[124:125], v[64:65], 0, v[130:131]
	ds_read_b128 v[150:153], v251 offset:21952
	ds_read_b128 v[154:157], v251 offset:30656
	v_lshl_add_u64 v[90:91], v[64:65], 0, v[24:25]
	ds_read_b128 v[162:165], v251 offset:26304
	s_waitcnt vmcnt(0) lgkmcnt(0)
	v_mfma_f32_16x16x32_bf16 v[50:53], v[54:57], v[72:75], v[50:53]
	v_lshl_add_u64 v[58:59], v[62:63], 0, v[130:131]
	v_lshl_add_u64 v[62:63], v[14:15], 0, s[4:5]
	v_mfma_f32_16x16x32_bf16 v[2:5], v[54:57], v[82:85], v[2:5]
	ds_read_b128 v[54:57], v12 offset:128
	s_mov_b64 s[4:5], 0xc0
	s_waitcnt lgkmcnt(0)
	v_mfma_f32_16x16x32_bf16 v[30:33], v[54:57], v[86:89], v[30:33]
	v_lshl_add_u64 v[58:59], v[62:63], 0, v[18:19]
	v_mfma_f32_16x16x32_bf16 v[6:9], v[54:57], v[92:95], v[6:9]
	v_lshl_add_u64 v[58:59], v[62:63], 0, v[16:17]
	v_mfma_f32_16x16x32_bf16 v[34:37], v[54:57], v[96:99], v[34:37]
	v_lshl_add_u64 v[58:59], v[62:63], 0, v[20:21]
	v_mfma_f32_16x16x32_bf16 v[38:41], v[54:57], v[100:103], v[38:41]
	v_lshl_add_u64 v[58:59], v[62:63], 0, v[22:23]
	v_mfma_f32_16x16x32_bf16 v[42:45], v[54:57], v[104:107], v[42:45]
	v_lshl_add_u64 v[58:59], v[62:63], 0, v[26:27]
	v_mfma_f32_16x16x32_bf16 v[46:49], v[54:57], v[108:111], v[46:49]
	v_lshl_add_u64 v[58:59], v[62:63], 0, v[24:25]
	v_mfma_f32_16x16x32_bf16 v[50:53], v[54:57], v[112:115], v[50:53]
	v_lshl_add_u64 v[58:59], v[62:63], 0, v[130:131]
	v_mov_b32_e32 v58, v116
	v_mov_b32_e32 v59, v117
	v_mov_b32_e32 v60, v118
	v_mov_b32_e32 v61, v119
	s_nop 1
	v_mfma_f32_16x16x32_bf16 v[2:5], v[54:57], v[58:61], v[2:5]
	ds_read_b128 v[54:57], v12 offset:192
	v_lshl_add_u64 v[58:59], v[14:15], 0, s[4:5]
	v_lshl_add_u64 v[14:15], v[58:59], 0, v[18:19]
	v_lshl_add_u64 v[18:19], v[58:59], 0, v[20:21]
	s_waitcnt lgkmcnt(0)
	v_mfma_f32_16x16x32_bf16 v[10:13], v[54:57], v[120:123], v[30:33]
	s_nop 2
	v_lshl_add_u64 v[14:15], v[58:59], 0, v[16:17]
	v_lshl_add_u64 v[22:23], v[58:59], 0, v[22:23]
	v_mfma_f32_16x16x32_bf16 v[6:9], v[54:57], v[138:141], v[6:9]
	v_lshl_add_u64 v[22:23], v[58:59], 0, v[26:27]
	v_lshl_add_u64 v[26:27], v[58:59], 0, v[130:131]
	v_mfma_f32_16x16x32_bf16 v[14:17], v[54:57], v[142:145], v[34:37]
	s_nop 2
	v_mfma_f32_16x16x32_bf16 v[18:21], v[54:57], v[126:129], v[38:41]
	s_nop 2
	v_mov_b32_e32 v38, v154
	v_mov_b32_e32 v39, v155
	v_mov_b32_e32 v40, v156
	v_mov_b32_e32 v41, v157
	v_lshl_add_u64 v[22:23], v[58:59], 0, v[24:25]
	v_add_u32_e32 v26, s1, v29
	v_lshl_or_b32 v26, v1, 2, v26
	v_or_b32_e32 v1, s0, v28
	v_mfma_f32_16x16x32_bf16 v[30:33], v[54:57], v[146:149], v[42:45]
	v_ashrrev_i32_e32 v27, 31, v26
	v_lshlrev_b32_e32 v130, 9, v1
	s_mov_b32 s0, 0x3d800000
	v_lshl_add_u64 v[28:29], v[26:27], 0, v[130:131]
	v_pk_mul_f32 v[10:11], v[10:11], s[0:1] op_sel_hi:[1,0]
	v_pk_mul_f32 v[12:13], v[12:13], s[0:1] op_sel_hi:[1,0]
	v_cvt_pk_bf16_f32 v10, v10, v11
	v_cvt_pk_bf16_f32 v11, v12, v13
	v_lshlrev_b64 v[12:13], 1, v[28:29]
	v_lshl_add_u64 v[28:29], s[6:7], 0, v[12:13]
	global_store_dwordx2 v[28:29], v[10:11], off
	v_pk_mul_f32 v[10:11], v[30:31], s[0:1] op_sel_hi:[1,0]
	v_pk_mul_f32 v[28:29], v[32:33], s[0:1] op_sel_hi:[1,0]
	v_cvt_pk_bf16_f32 v10, v10, v11
	v_cvt_pk_bf16_f32 v11, v28, v29
	v_lshl_add_u64 v[12:13], s[8:9], 0, v[12:13]
	v_mfma_f32_16x16x32_bf16 v[34:37], v[54:57], v[150:153], v[46:49]
	global_store_dwordx2 v[12:13], v[10:11], off
	v_or_b32_e32 v10, 0x2000, v130
	v_mov_b32_e32 v11, v131
	v_lshl_add_u64 v[10:11], v[10:11], 0, v[26:27]
	v_pk_mul_f32 v[6:7], v[6:7], s[0:1] op_sel_hi:[1,0]
	v_pk_mul_f32 v[8:9], v[8:9], s[0:1] op_sel_hi:[1,0]
	v_cvt_pk_bf16_f32 v6, v6, v7
	v_cvt_pk_bf16_f32 v7, v8, v9
	v_lshlrev_b64 v[8:9], 1, v[10:11]
	v_lshl_add_u64 v[10:11], s[6:7], 0, v[8:9]
	global_store_dwordx2 v[10:11], v[6:7], off
	v_pk_mul_f32 v[6:7], v[34:35], s[0:1] op_sel_hi:[1,0]
	v_pk_mul_f32 v[10:11], v[36:37], s[0:1] op_sel_hi:[1,0]
	v_cvt_pk_bf16_f32 v6, v6, v7
	v_cvt_pk_bf16_f32 v7, v10, v11
	v_lshl_add_u64 v[8:9], s[8:9], 0, v[8:9]
	v_mfma_f32_16x16x32_bf16 v[22:25], v[54:57], v[162:165], v[50:53]
	global_store_dwordx2 v[8:9], v[6:7], off
	v_or_b32_e32 v6, 0x4000, v130
	v_mov_b32_e32 v7, v131
	v_lshl_add_u64 v[6:7], v[6:7], 0, v[26:27]
	v_pk_mul_f32 v[8:9], v[14:15], s[0:1] op_sel_hi:[1,0]
	v_pk_mul_f32 v[10:11], v[16:17], s[0:1] op_sel_hi:[1,0]
	v_lshlrev_b64 v[6:7], 1, v[6:7]
	v_mfma_f32_16x16x32_bf16 v[2:5], v[54:57], v[38:41], v[2:5]
	v_cvt_pk_bf16_f32 v8, v8, v9
	v_cvt_pk_bf16_f32 v9, v10, v11
	v_lshl_add_u64 v[10:11], s[6:7], 0, v[6:7]
	global_store_dwordx2 v[10:11], v[8:9], off
	v_pk_mul_f32 v[8:9], v[22:23], s[0:1] op_sel_hi:[1,0]
	v_pk_mul_f32 v[10:11], v[24:25], s[0:1] op_sel_hi:[1,0]
	v_cvt_pk_bf16_f32 v8, v8, v9
	v_cvt_pk_bf16_f32 v9, v10, v11
	v_lshl_add_u64 v[6:7], s[8:9], 0, v[6:7]
	v_or_b32_e32 v130, 0x6000, v130
	global_store_dwordx2 v[6:7], v[8:9], off
	v_lshl_add_u64 v[6:7], v[130:131], 0, v[26:27]
	v_pk_mul_f32 v[8:9], v[18:19], s[0:1] op_sel_hi:[1,0]
	v_pk_mul_f32 v[10:11], v[20:21], s[0:1] op_sel_hi:[1,0]
	v_lshlrev_b64 v[6:7], 1, v[6:7]
	v_pk_mul_f32 v[2:3], v[2:3], s[0:1] op_sel_hi:[1,0]
	v_pk_mul_f32 v[4:5], v[4:5], s[0:1] op_sel_hi:[1,0]
	v_cvt_pk_bf16_f32 v8, v8, v9
	v_cvt_pk_bf16_f32 v9, v10, v11
	v_lshl_add_u64 v[10:11], s[6:7], 0, v[6:7]
	v_cvt_pk_bf16_f32 v2, v2, v3
	v_cvt_pk_bf16_f32 v3, v4, v5
	v_lshl_add_u64 v[4:5], s[8:9], 0, v[6:7]
	global_store_dwordx2 v[10:11], v[8:9], off
	global_store_dwordx2 v[4:5], v[2:3], off

.LBB0_416:
	s_andn2_b64 vcc, exec, s[0:1]
	s_cbranch_vccnz .LBB0_418
	s_lshl_b32 s0, s2, 3
	s_add_i32 s0, s0, 0x7fffba00
	v_mov_b32_e32 v18, v0
	s_and_b32 s0, s0, 0x7fffffc0
	s_lshl_b32 s1, s2, 6
	v_lshlrev_b32_e32 v1, 3, v18
	s_waitcnt vmcnt(0) lgkmcnt(0)
	v_ashrrev_i32_e32 v64, 3, v18
	s_and_b32 s18, s1, 0x1c0
	v_and_b32_e32 v65, 56, v1
	v_add_u32_e32 v72, s0, v64
	v_add_u32_e32 v64, 0x100, v18
	v_or_b32_e32 v73, s18, v65
	v_ashrrev_i32_e32 v65, 31, v72
	v_ashrrev_i32_e32 v74, 3, v64
	v_mov_b32_e32 v82, v72
	v_mov_b32_e32 v83, v65
	v_lshlrev_b64 v[84:85], 10, v[82:83]
	v_lshlrev_b32_e32 v64, 1, v73
	v_readlane_b32 s18, v253, 53
	v_add_u32_e32 v65, s0, v74
	v_or_b32_e32 v72, v84, v64
	v_readlane_b32 s19, v253, 54
	v_ashrrev_i32_e32 v73, 31, v65
	v_mov_b32_e32 v74, v65
	v_mov_b32_e32 v75, v73
	v_lshlrev_b64 v[82:83], 10, v[74:75]
	v_mov_b32_e32 v74, v72
	v_mov_b32_e32 v75, v85
	v_lshl_add_u64 v[86:87], s[18:19], 0, v[74:75]
	global_load_dwordx4 v[88:91], v[86:87], off
	v_or_b32_e32 v65, v82, v64
	v_mov_b32_e32 v74, v65
	v_mov_b32_e32 v75, v83
	v_lshl_add_u64 v[86:87], s[18:19], 0, v[74:75]
	global_load_dwordx4 v[92:95], v[86:87], off
	v_readlane_b32 s18, v254, 7
	v_readlane_b32 s19, v254, 8
	v_mov_b32_e32 v74, v72
	v_mov_b32_e32 v75, v85
	v_lshl_add_u64 v[86:87], s[18:19], 0, v[74:75]
	global_load_dwordx4 v[72:75], v[86:87], off
	v_mov_b32_e32 v84, v65
	v_mov_b32_e32 v85, v83
	v_lshl_add_u64 v[86:87], s[18:19], 0, v[84:85]
	global_load_dwordx4 v[82:85], v[86:87], off
	v_bfe_u32 v64, v18, 4, 2
	v_lshlrev_b32_e32 v65, 4, v64
	v_and_b32_e32 v64, 15, v18
	v_readlane_b32 s18, v253, 43
	v_readlane_b32 s19, v253, 44
	v_mov_b32_e32 v76, v131
	v_mov_b32_e32 v86, v65
	v_mov_b32_e32 v87, v131
	v_lshl_add_u64 v[96:97], s[18:19], 0, v[86:87]
	v_lshlrev_b32_e32 v65, 8, v64
	v_or_b32_e32 v64, 0x2000, v65
	v_mov_b32_e32 v86, v65
	v_mov_b32_e32 v87, v131
	v_lshl_add_u64 v[98:99], v[96:97], 0, v[86:87]
	v_mov_b32_e32 v86, v64
	v_mov_b32_e32 v87, v76
	v_lshl_add_u64 v[100:101], v[96:97], 0, v[86:87]
	v_and_b32_e32 v251, 15, v0
	v_mul_u32_u24_e32 v251, 0x110, v251
	v_bfe_u32 v250, v0, 4, 2
	v_lshl_add_u32 v251, v250, 4, v251
	v_add_u32_e32 v251, 0x9800, v251
	ds_read_b128 v[102:105], v251
	ds_read_b128 v[106:109], v251 offset:8704
	v_or_b32_e32 v78, 0x1000, v65
	v_mov_b32_e32 v86, v131
	v_lshl_add_u64 v[100:101], v[96:97], 0, 64
	v_mov_b32_e32 v110, v78
	v_mov_b32_e32 v111, v86
	v_lshl_add_u64 v[112:113], v[96:97], 0, v[110:111]
	ds_read_b128 v[114:117], v251 offset:4352
	ds_read_b128 v[110:113], v251 offset:64
	v_or_b32_e32 v87, 0x3000, v65
	v_mov_b32_e32 v98, v131
	v_mov_b32_e32 v118, v87
	v_mov_b32_e32 v119, v98
	v_lshl_add_u64 v[120:121], v[96:97], 0, v[118:119]
	ds_read_b128 v[122:125], v251 offset:13056
	v_or_b32_e32 v99, 0x4000, v65
	v_mov_b32_e32 v118, v131
	v_mov_b32_e32 v120, v99
	v_mov_b32_e32 v121, v118
	v_lshl_add_u64 v[126:127], v[96:97], 0, v[120:121]
	ds_read_b128 v[138:141], v251 offset:17408
	v_or_b32_e32 v119, 0x5000, v65
	v_mov_b32_e32 v120, v131
	v_mov_b32_e32 v126, v119
	v_mov_b32_e32 v127, v120
	v_lshl_add_u64 v[128:129], v[96:97], 0, v[126:127]
	ds_read_b128 v[142:145], v251 offset:21760
	v_or_b32_e32 v121, 0x6000, v65
	v_mov_b32_e32 v126, v131
	v_or_b32_e32 v127, 0x7000, v65
	v_mov_b32_e32 v128, v121
	v_mov_b32_e32 v129, v126
	v_lshl_add_u64 v[146:147], v[96:97], 0, v[128:129]
	v_mov_b32_e32 v128, v127
	v_mov_b32_e32 v129, v131
	v_lshl_add_u64 v[148:149], v[96:97], 0, v[128:129]
	ds_read_b128 v[126:129], v251 offset:26112
	ds_read_b128 v[150:153], v251 offset:30464
	v_mov_b32_e32 v96, v78
	v_mov_b32_e32 v97, v86
	v_lshl_add_u64 v[146:147], v[100:101], 0, v[96:97]
	ds_read_b128 v[154:157], v251 offset:4416
	v_mov_b32_e32 v96, v64
	v_mov_b32_e32 v97, v76
	v_lshl_add_u64 v[146:147], v[100:101], 0, v[96:97]
	ds_read_b128 v[162:165], v251 offset:8768
	v_mov_b32_e32 v64, v87
	v_mov_b32_e32 v65, v98
	v_lshl_add_u64 v[96:97], v[100:101], 0, v[64:65]
	ds_read_b128 v[146:149], v251 offset:13120
	v_mov_b32_e32 v64, v99
	v_mov_b32_e32 v65, v118
	v_lshl_add_u64 v[86:87], v[100:101], 0, v[64:65]
	ds_read_b128 v[96:99], v251 offset:17472
	v_mov_b32_e32 v64, v119
	v_mov_b32_e32 v65, v120
	v_lshl_add_u64 v[86:87], v[100:101], 0, v[64:65]
	ds_read_b128 v[118:121], v251 offset:21824
	v_ashrrev_i32_e32 v20, 3, v18
	s_and_b32 s1, s1, 0x1c0
	v_and_b32_e32 v19, 56, v1
	v_add_u32_e32 v2, s0, v20
	v_add_u32_e32 v10, 0x100, v18
	v_or_b32_e32 v1, s1, v19
	v_ashrrev_i32_e32 v3, 31, v2
	v_ashrrev_i32_e32 v21, 3, v10
	v_lshlrev_b64 v[6:7], 10, v[2:3]
	v_lshlrev_b32_e32 v1, 1, v1
	v_readlane_b32 s6, v253, 53
	v_add_u32_e32 v10, s0, v21
	v_or_b32_e32 v6, v6, v1
	v_readlane_b32 s7, v253, 54
	v_ashrrev_i32_e32 v11, 31, v10
	v_lshlrev_b64 v[14:15], 10, v[10:11]
	v_lshl_add_u64 v[2:3], s[6:7], 0, v[6:7]
	v_or_b32_e32 v14, v14, v1
	v_lshl_add_u64 v[10:11], s[6:7], 0, v[14:15]
	v_readlane_b32 s8, v254, 7
	v_readlane_b32 s9, v254, 8
	v_lshlrev_b32_e32 v20, 1, v20
	s_movk_i32 s3, 0x110
	v_lshl_add_u64 v[6:7], s[8:9], 0, v[6:7]
	v_lshl_add_u64 v[14:15], s[8:9], 0, v[14:15]
	v_mad_u32_u24 v20, v19, s3, v20
	s_barrier
	v_bfe_u32 v1, v18, 4, 2
	v_lshlrev_b32_e32 v130, 4, v1
	v_and_b32_e32 v28, 15, v18
	s_waitcnt vmcnt(0) lgkmcnt(0)
	ds_write_b16 v20, v88
	ds_write_b16_d16_hi v20, v88 offset:272
	ds_write_b16 v20, v89 offset:544
	ds_write_b16_d16_hi v20, v89 offset:816
	ds_write_b16 v20, v90 offset:1088
	ds_write_b16_d16_hi v20, v90 offset:1360
	ds_write_b16 v20, v91 offset:1632
	ds_write_b16_d16_hi v20, v91 offset:1904
	ds_write_b16 v20, v72 offset:128
	ds_write_b16_d16_hi v20, v72 offset:400
	ds_write_b16 v20, v73 offset:672
	ds_write_b16_d16_hi v20, v73 offset:944
	ds_write_b16 v20, v74 offset:1216
	ds_write_b16_d16_hi v20, v74 offset:1488
	ds_write_b16 v20, v75 offset:1760
	ds_write_b16_d16_hi v20, v75 offset:2032
	v_lshlrev_b32_e32 v2, 1, v21
	v_mad_u32_u24 v2, v19, s3, v2
	ds_write_b16 v2, v92
	ds_write_b16_d16_hi v2, v92 offset:272
	ds_write_b16 v2, v93 offset:544
	ds_write_b16_d16_hi v2, v93 offset:816
	ds_write_b16 v2, v94 offset:1088
	ds_write_b16_d16_hi v2, v94 offset:1360
	ds_write_b16 v2, v95 offset:1632
	ds_write_b16_d16_hi v2, v95 offset:1904
	ds_write_b16 v2, v82 offset:128
	ds_write_b16_d16_hi v2, v82 offset:400
	ds_write_b16 v2, v83 offset:672
	ds_write_b16_d16_hi v2, v83 offset:944
	ds_write_b16 v2, v84 offset:1216
	ds_write_b16_d16_hi v2, v84 offset:1488
	ds_write_b16 v2, v85 offset:1760
	ds_write_b16_d16_hi v2, v85 offset:2032
	v_ashrrev_i32_e32 v2, 2, v18
	v_and_b32_e32 v29, -16, v2
	v_bfi_b32 v2, -16, v2, v18
	v_mad_u64_u32 v[12:13], s[4:5], v2, s3, v[130:131]
	v_readlane_b32 s4, v253, 43
	v_readlane_b32 s5, v253, 44
	v_mov_b32_e32 v17, v131
	s_waitcnt lgkmcnt(0)
	v_lshl_add_u64 v[14:15], s[4:5], 0, v[130:131]
	v_lshlrev_b32_e32 v130, 8, v28
	v_or_b32_e32 v16, 0x2000, v130
	v_lshl_add_u64 v[10:11], v[14:15], 0, v[130:131]
	v_lshl_add_u64 v[20:21], v[14:15], 0, v[16:17]
	s_barrier
	ds_read_b128 v[2:5], v12
	v_or_b32_e32 v18, 0x1000, v130
	v_mov_b32_e32 v19, v131
	v_lshl_add_u64 v[62:63], v[14:15], 0, 64
	s_mov_b64 s[4:5], 0x80
	s_waitcnt lgkmcnt(0)
	v_mfma_f32_16x16x32_bf16 v[30:33], v[2:5], v[102:105], 0
	v_lshl_add_u64 v[6:7], v[14:15], 0, v[18:19]
	s_nop 0
	v_mfma_f32_16x16x32_bf16 v[34:37], v[2:5], v[106:109], 0
	v_or_b32_e32 v20, 0x3000, v130
	v_mov_b32_e32 v21, v131
	v_lshl_add_u64 v[22:23], v[14:15], 0, v[20:21]
	v_mfma_f32_16x16x32_bf16 v[6:9], v[2:5], v[114:117], 0
	v_mfma_f32_16x16x32_bf16 v[38:41], v[2:5], v[122:125], 0
	v_or_b32_e32 v22, 0x4000, v130
	v_mov_b32_e32 v23, v131
	v_lshl_add_u64 v[24:25], v[14:15], 0, v[22:23]
	v_mfma_f32_16x16x32_bf16 v[42:45], v[2:5], v[138:141], 0
	v_or_b32_e32 v26, 0x5000, v130
	v_mov_b32_e32 v27, v131
	v_lshl_add_u64 v[24:25], v[14:15], 0, v[26:27]
	v_or_b32_e32 v24, 0x6000, v130
	v_mov_b32_e32 v25, v131
	v_or_b32_e32 v130, 0x7000, v130
	v_lshl_add_u64 v[50:51], v[14:15], 0, v[24:25]
	v_lshl_add_u64 v[54:55], v[14:15], 0, v[130:131]
	v_mfma_f32_16x16x32_bf16 v[46:49], v[2:5], v[142:145], 0
	v_mfma_f32_16x16x32_bf16 v[50:53], v[2:5], v[126:129], 0
	v_mfma_f32_16x16x32_bf16 v[2:5], v[2:5], v[150:153], 0
	ds_read_b128 v[54:57], v12 offset:64
	s_waitcnt lgkmcnt(0)
	v_mfma_f32_16x16x32_bf16 v[30:33], v[54:57], v[110:113], v[30:33]
	v_lshl_add_u64 v[58:59], v[62:63], 0, v[18:19]
	v_mfma_f32_16x16x32_bf16 v[6:9], v[54:57], v[154:157], v[6:9]
	v_lshl_add_u64 v[58:59], v[62:63], 0, v[16:17]
	v_mfma_f32_16x16x32_bf16 v[34:37], v[54:57], v[162:165], v[34:37]
	v_lshl_add_u64 v[58:59], v[62:63], 0, v[20:21]
	v_mfma_f32_16x16x32_bf16 v[38:41], v[54:57], v[146:149], v[38:41]
	v_lshl_add_u64 v[58:59], v[62:63], 0, v[22:23]
	v_mfma_f32_16x16x32_bf16 v[42:45], v[54:57], v[96:99], v[42:45]
	v_lshl_add_u64 v[58:59], v[62:63], 0, v[26:27]
	v_mfma_f32_16x16x32_bf16 v[46:49], v[54:57], v[118:121], v[46:49]
	v_lshl_add_u64 v[58:59], v[62:63], 0, v[24:25]
	ds_read_b128 v[72:75], v251 offset:26176
	v_lshl_add_u64 v[64:65], v[62:63], 0, v[130:131]
	ds_read_b128 v[82:85], v251 offset:30528
	v_lshl_add_u64 v[64:65], v[14:15], 0, s[4:5]
	ds_read_b128 v[86:89], v251 offset:128
	s_mov_b64 s[18:19], 0xc0
	v_lshl_add_u64 v[90:91], v[64:65], 0, v[18:19]
	ds_read_b128 v[92:95], v251 offset:4480
	v_lshl_add_u64 v[90:91], v[64:65], 0, v[16:17]
	ds_read_b128 v[96:99], v251 offset:8832
	v_lshl_add_u64 v[90:91], v[64:65], 0, v[20:21]
	ds_read_b128 v[100:103], v251 offset:13184
	v_lshl_add_u64 v[90:91], v[64:65], 0, v[22:23]
	ds_read_b128 v[104:107], v251 offset:17536
	v_lshl_add_u64 v[90:91], v[64:65], 0, v[26:27]
	ds_read_b128 v[108:111], v251 offset:21888
	v_lshl_add_u64 v[90:91], v[64:65], 0, v[24:25]
	ds_read_b128 v[112:115], v251 offset:26240
	v_lshl_add_u64 v[90:91], v[64:65], 0, v[130:131]
	ds_read_b128 v[116:119], v251 offset:30592
	ds_read_b128 v[120:123], v251 offset:192
	v_lshl_add_u64 v[64:65], v[14:15], 0, s[18:19]
	v_lshl_add_u64 v[90:91], v[64:65], 0, v[18:19]
	v_lshl_add_u64 v[124:125], v[64:65], 0, v[20:21]
	ds_read_b128 v[126:129], v251 offset:13248
	ds_read_b128 v[138:141], v251 offset:4544
	v_lshl_add_u64 v[90:91], v[64:65], 0, v[16:17]
	ds_read_b128 v[142:145], v251 offset:8896
	v_lshl_add_u64 v[90:91], v[64:65], 0, v[22:23]
	ds_read_b128 v[146:149], v251 offset:17600
	v_lshl_add_u64 v[90:91], v[64:65], 0, v[26:27]
	v_lshl_add_u64 v[124:125], v[64:65], 0, v[130:131]
	ds_read_b128 v[150:153], v251 offset:21952
	ds_read_b128 v[154:157], v251 offset:30656
	v_lshl_add_u64 v[90:91], v[64:65], 0, v[24:25]
	ds_read_b128 v[162:165], v251 offset:26304
	s_waitcnt vmcnt(0) lgkmcnt(0)
	v_mfma_f32_16x16x32_bf16 v[50:53], v[54:57], v[72:75], v[50:53]
	v_lshl_add_u64 v[58:59], v[62:63], 0, v[130:131]
	v_lshl_add_u64 v[62:63], v[14:15], 0, s[4:5]
	v_mfma_f32_16x16x32_bf16 v[2:5], v[54:57], v[82:85], v[2:5]
	ds_read_b128 v[54:57], v12 offset:128
	s_mov_b64 s[4:5], 0xc0
	s_waitcnt lgkmcnt(0)
	v_mfma_f32_16x16x32_bf16 v[30:33], v[54:57], v[86:89], v[30:33]
	v_lshl_add_u64 v[58:59], v[62:63], 0, v[18:19]
	v_mfma_f32_16x16x32_bf16 v[6:9], v[54:57], v[92:95], v[6:9]
	v_lshl_add_u64 v[58:59], v[62:63], 0, v[16:17]
	v_mfma_f32_16x16x32_bf16 v[34:37], v[54:57], v[96:99], v[34:37]
	v_lshl_add_u64 v[58:59], v[62:63], 0, v[20:21]
	v_mfma_f32_16x16x32_bf16 v[38:41], v[54:57], v[100:103], v[38:41]
	v_lshl_add_u64 v[58:59], v[62:63], 0, v[22:23]
	v_mfma_f32_16x16x32_bf16 v[42:45], v[54:57], v[104:107], v[42:45]
	v_lshl_add_u64 v[58:59], v[62:63], 0, v[26:27]
	v_mfma_f32_16x16x32_bf16 v[46:49], v[54:57], v[108:111], v[46:49]
	v_lshl_add_u64 v[58:59], v[62:63], 0, v[24:25]
	v_mfma_f32_16x16x32_bf16 v[50:53], v[54:57], v[112:115], v[50:53]
	v_lshl_add_u64 v[58:59], v[62:63], 0, v[130:131]
	v_mov_b32_e32 v58, v116
	v_mov_b32_e32 v59, v117
	v_mov_b32_e32 v60, v118
	v_mov_b32_e32 v61, v119
	s_nop 1
	v_mfma_f32_16x16x32_bf16 v[2:5], v[54:57], v[58:61], v[2:5]
	ds_read_b128 v[54:57], v12 offset:192
	v_lshl_add_u64 v[58:59], v[14:15], 0, s[4:5]
	v_lshl_add_u64 v[14:15], v[58:59], 0, v[18:19]
	v_lshl_add_u64 v[18:19], v[58:59], 0, v[20:21]
	s_waitcnt lgkmcnt(0)
	v_mfma_f32_16x16x32_bf16 v[10:13], v[54:57], v[120:123], v[30:33]
	s_nop 2
	v_lshl_add_u64 v[14:15], v[58:59], 0, v[16:17]
	v_lshl_add_u64 v[22:23], v[58:59], 0, v[22:23]
	v_mfma_f32_16x16x32_bf16 v[6:9], v[54:57], v[138:141], v[6:9]
	v_lshl_add_u64 v[22:23], v[58:59], 0, v[26:27]
	v_lshl_add_u64 v[26:27], v[58:59], 0, v[130:131]
	v_mfma_f32_16x16x32_bf16 v[14:17], v[54:57], v[142:145], v[34:37]
	s_nop 2
	v_mfma_f32_16x16x32_bf16 v[18:21], v[54:57], v[126:129], v[38:41]
	s_nop 2
	v_mov_b32_e32 v38, v154
	v_mov_b32_e32 v39, v155
	v_mov_b32_e32 v40, v156
	v_mov_b32_e32 v41, v157
	v_lshl_add_u64 v[22:23], v[58:59], 0, v[24:25]
	v_add_u32_e32 v26, s1, v29
	v_lshl_or_b32 v26, v1, 2, v26
	v_or_b32_e32 v1, s0, v28
	v_mfma_f32_16x16x32_bf16 v[30:33], v[54:57], v[146:149], v[42:45]
	v_ashrrev_i32_e32 v27, 31, v26
	v_lshlrev_b32_e32 v130, 9, v1
	s_mov_b32 s0, 0x3c800000
	v_lshl_add_u64 v[28:29], v[26:27], 0, v[130:131]
	v_pk_mul_f32 v[10:11], v[10:11], s[0:1] op_sel_hi:[1,0]
	v_pk_mul_f32 v[12:13], v[12:13], s[0:1] op_sel_hi:[1,0]
	v_cvt_pk_bf16_f32 v10, v10, v11
	v_cvt_pk_bf16_f32 v11, v12, v13
	v_lshlrev_b64 v[12:13], 1, v[28:29]
	v_lshl_add_u64 v[28:29], s[6:7], 0, v[12:13]
	global_store_dwordx2 v[28:29], v[10:11], off
	v_pk_mul_f32 v[10:11], v[30:31], s[0:1] op_sel_hi:[1,0]
	v_pk_mul_f32 v[28:29], v[32:33], s[0:1] op_sel_hi:[1,0]
	v_cvt_pk_bf16_f32 v10, v10, v11
	v_cvt_pk_bf16_f32 v11, v28, v29
	v_lshl_add_u64 v[12:13], s[8:9], 0, v[12:13]
	v_mfma_f32_16x16x32_bf16 v[34:37], v[54:57], v[150:153], v[46:49]
	global_store_dwordx2 v[12:13], v[10:11], off
	v_or_b32_e32 v10, 0x2000, v130
	v_mov_b32_e32 v11, v131
	v_lshl_add_u64 v[10:11], v[10:11], 0, v[26:27]
	v_pk_mul_f32 v[6:7], v[6:7], s[0:1] op_sel_hi:[1,0]
	v_pk_mul_f32 v[8:9], v[8:9], s[0:1] op_sel_hi:[1,0]
	v_cvt_pk_bf16_f32 v6, v6, v7
	v_cvt_pk_bf16_f32 v7, v8, v9
	v_lshlrev_b64 v[8:9], 1, v[10:11]
	v_lshl_add_u64 v[10:11], s[6:7], 0, v[8:9]
	global_store_dwordx2 v[10:11], v[6:7], off
	v_pk_mul_f32 v[6:7], v[34:35], s[0:1] op_sel_hi:[1,0]
	v_pk_mul_f32 v[10:11], v[36:37], s[0:1] op_sel_hi:[1,0]
	v_cvt_pk_bf16_f32 v6, v6, v7
	v_cvt_pk_bf16_f32 v7, v10, v11
	v_lshl_add_u64 v[8:9], s[8:9], 0, v[8:9]
	v_mfma_f32_16x16x32_bf16 v[22:25], v[54:57], v[162:165], v[50:53]
	global_store_dwordx2 v[8:9], v[6:7], off
	v_or_b32_e32 v6, 0x4000, v130
	v_mov_b32_e32 v7, v131
	v_lshl_add_u64 v[6:7], v[6:7], 0, v[26:27]
	v_pk_mul_f32 v[8:9], v[14:15], s[0:1] op_sel_hi:[1,0]
	v_pk_mul_f32 v[10:11], v[16:17], s[0:1] op_sel_hi:[1,0]
	v_lshlrev_b64 v[6:7], 1, v[6:7]
	v_mfma_f32_16x16x32_bf16 v[2:5], v[54:57], v[38:41], v[2:5]
	v_cvt_pk_bf16_f32 v8, v8, v9
	v_cvt_pk_bf16_f32 v9, v10, v11
	v_lshl_add_u64 v[10:11], s[6:7], 0, v[6:7]
	global_store_dwordx2 v[10:11], v[8:9], off
	v_pk_mul_f32 v[8:9], v[22:23], s[0:1] op_sel_hi:[1,0]
	v_pk_mul_f32 v[10:11], v[24:25], s[0:1] op_sel_hi:[1,0]
	v_cvt_pk_bf16_f32 v8, v8, v9
	v_cvt_pk_bf16_f32 v9, v10, v11
	v_lshl_add_u64 v[6:7], s[8:9], 0, v[6:7]
	v_or_b32_e32 v130, 0x6000, v130
	global_store_dwordx2 v[6:7], v[8:9], off
	v_lshl_add_u64 v[6:7], v[130:131], 0, v[26:27]
	v_pk_mul_f32 v[8:9], v[18:19], s[0:1] op_sel_hi:[1,0]
	v_pk_mul_f32 v[10:11], v[20:21], s[0:1] op_sel_hi:[1,0]
	v_lshlrev_b64 v[6:7], 1, v[6:7]
	v_pk_mul_f32 v[2:3], v[2:3], s[0:1] op_sel_hi:[1,0]
	v_pk_mul_f32 v[4:5], v[4:5], s[0:1] op_sel_hi:[1,0]
	v_cvt_pk_bf16_f32 v8, v8, v9
	v_cvt_pk_bf16_f32 v9, v10, v11
	v_lshl_add_u64 v[10:11], s[6:7], 0, v[6:7]
	v_cvt_pk_bf16_f32 v2, v2, v3
	v_cvt_pk_bf16_f32 v3, v4, v5
	v_lshl_add_u64 v[4:5], s[8:9], 0, v[6:7]
	global_store_dwordx2 v[10:11], v[8:9], off
	global_store_dwordx2 v[4:5], v[2:3], off
